# lora GEMM units reassigned by epilogue cost: single-unit workgroups take decay tiles, pairs are decay+gate or a_lr+gate, cumsum workgroups take no GEMM unit
# speedup vs baseline: 1.0084x; 1.0084x over previous
.LBB0_763:
	s_cmpk_lt_i32 s2, 0xfe
	s_cselect_b64 s[0:1], -1, 0
	s_cmpk_gt_i32 s2, 0xfd
	v_readfirstlane_b32 s18, v166
	s_cbranch_scc1 .LBB0_769
	s_cmp_lt_u32 s2, 20
	s_cbranch_scc1 .Lp3_a
	s_cmp_lt_u32 s2, 0x8e
	s_cbranch_scc1 .Lp3_b
	s_add_i32 s3, s2, 0xffffff72
	s_mov_b32 s4, 0
	s_branch .Lp3_j
.Lp3_a:
	s_add_i32 s3, s2, 0x70
	s_mov_b32 s4, 0
	s_branch .Lp3_j
.Lp3_b:
	s_add_i32 s3, s2, 0xffffffec
	s_mov_b32 s4, 4
.Lp3_j:
	s_mul_hi_u32 s5, s3, 0x7c1f07d
	s_mul_i32 s8, s5, 33
	s_sub_i32 s20, s3, s8
	s_add_i32 s21, s4, s5

.LBB0_772:
	s_add_u32 s10, s94, 0x10400000
	s_addc_u32 s11, s95, 0
	s_add_u32 s12, s94, 0x12500000
	s_addc_u32 s13, s95, 0
	s_add_u32 s14, s94, 0x800000
	v_lshl_or_b32 v160, s0, 6, v8
	v_lshlrev_b32_e32 v14, 6, v8
	v_lshlrev_b32_e32 v15, 1, v11
	s_movk_i32 s4, 0x3c0
	v_lshlrev_b32_e32 v8, 2, v8
	s_addc_u32 s15, s95, 0
	v_and_or_b32 v14, v14, s4, v15
	s_lshl_b32 s0, s0, 13
	v_and_b32_e32 v8, 32, v8
	v_bitop3_b32 v8, v14, s0, v8 bitop3:0xde
	s_lshl_b32 s0, s1, 5
	v_lshlrev_b32_e32 v14, 6, v166
	s_mov_b64 s[16:17], 0x80
	s_and_b32 s5, s0, 0x60
	v_and_or_b32 v14, v14, s4, v15
	v_lshlrev_b32_e32 v15, 2, v166
	s_add_i32 m0, s52, 0x18000
	v_lshl_add_u64 v[6:7], v[6:7], 0, s[16:17]
	s_lshl_b32 s0, s5, 7
	v_and_b32_e32 v15, 32, v15
	s_waitcnt vmcnt(2)
	s_barrier
	global_load_lds_dwordx4 v[6:7], off
	v_lshl_add_u64 v[4:5], v[4:5], 0, s[16:17]
	s_add_i32 m0, s52, 0x1a000
	s_add_i32 s62, s52, 0x8000
	s_add_i32 s63, s52, 0xa000
	v_bitop3_b32 v161, s0, v14, v15 bitop3:0xf6
	global_load_lds_dwordx4 v[4:5], off
	v_lshl_add_u64 v[0:1], v[0:1], 0, s[16:17]
	s_mov_b32 m0, s62
	s_add_u32 s0, s34, 0x18080
	global_load_lds_dwordx4 v[0:1], off
	v_lshl_add_u64 v[0:1], v[2:3], 0, s[16:17]
	s_mov_b32 m0, s63
	s_addc_u32 s1, s35, 0
	global_load_lds_dwordx4 v[0:1], off
	s_add_i32 m0, s52, 0x1c000
	v_lshl_add_u64 v[0:1], s[0:1], 0, v[138:139]
	global_load_lds_dwordx4 v[0:1], off
	v_lshl_add_u64 v[0:1], s[0:1], 0, v[142:143]
	s_add_i32 m0, s52, 0x1e000
	s_cmpk_lt_u32 s18, 0x100
	global_load_lds_dwordx4 v[0:1], off
	s_waitcnt vmcnt(6)
	v_add_u16_e32 v0, v9, v10
	s_cselect_b64 s[18:19], -1, 0
	v_lshrrev_b16_e32 v0, 1, v0
	s_add_i32 s66, 0, 0x10000
	s_add_i32 s67, 0, 0x14000
	s_ashr_i32 s64, s33, 31
	s_ashr_i32 s65, s2, 31
	v_or_b32_e32 v162, s5, v11
	v_add_lshl_u32 v144, v12, v0, 1
	v_mov_b32_e32 v145, v139
	v_add_lshl_u32 v146, v13, v0, 1
	v_mov_b32_e32 v147, v139
	v_mov_b64_e32 v[148:149], 0x18e
	v_mov_b64_e32 v[150:151], 0x18d
	v_add_u32_e32 v163, s66, v161
	v_add_u32_e32 v164, s67, v161
	v_add_u32_e32 v165, 0, v8
	s_movk_i32 s36, 0x2080
	s_movk_i32 s37, 0x2070
	s_movk_i32 s38, 0x2060
	s_movk_i32 s39, 0x2050
	s_mov_b64 s[50:51], 0x40000
	s_movk_i32 s42, 0x1ff0
	s_mov_b64 s[56:57], 0x48000
	s_movk_i32 s43, 0x1fe0
	s_mov_b64 s[58:59], 0x50000
	s_movk_i32 s48, 0x1fd0
	s_mov_b64 s[84:85], 0x58000
	s_mov_b32 s49, 0xbfb8aa3b
	s_mov_b32 s90, 0x800000
	s_mov_b32 s91, 0x3f317217
	s_mov_b32 s96, 0x7f800000
	v_mov_b32_e32 v167, 0x41b17218
	s_barrier
	s_branch .LBB0_775

.LBB0_775:
	s_add_i32 s61, s61, 1
	s_mul_i32 s0, s61, s64
	s_mul_hi_u32 s1, s61, s33
	s_add_i32 s1, s1, s0
	s_mul_i32 s0, s61, s33
	s_add_u32 s4, s0, s2
	s_addc_u32 s5, s1, s65
	v_cmp_gt_i64_e32 vcc, s[4:5], v[150:151]
	v_cmp_lt_i64_e64 s[0:1], s[4:5], v[148:149]
	s_cbranch_vccnz .LBB0_781
	s_cmp_lt_u32 s4, 0x184
	s_cbranch_scc1 .Lp3_l2
	s_add_i32 s5, s4, 0xfffffef6
	s_mov_b32 s23, 4
	s_branch .Lp3_lj
.Lp3_l2:
	s_add_i32 s5, s4, 0xffffff00
	s_mov_b32 s23, 8
.Lp3_lj:
	s_mul_hi_u32 s24, s5, 0x7c1f07d
	s_mul_i32 s25, s24, 33
	s_sub_i32 s22, s5, s25
	s_add_i32 s97, s23, s24
